# expert-table conversion items moved out of the P3 queue into idle blocks at the ends of P4/P5/P6 (one item per idle block, static assignment)
# speedup vs baseline: 1.0063x; 1.0050x over previous
.LBB0_559:
	s_andn2_b64 vcc, exec, s[42:43]
	s_branch .LBB0_440
	s_lshl_b32 s12, s50, 2
	v_lshl_or_b32 v34, s50, 4, v180
	s_mov_b32 s13, 0
	s_branch .LBB0_563

.LBB0_658:
	s_cmp_lt_u32 s2, 0x80
	s_cbranch_scc1 .Lcv_ret_p4
	s_load_dwordx4 s[48:51], s[0:1], 0xf0
	v_mov_b32_e32 v1, 0
	v_and_b32_e32 v2, 63, v204
	v_lshlrev_b32_e32 v0, 6, v2
	v_lshrrev_b32_e32 v180, 6, v204
	v_lshlrev_b32_e32 v168, 3, v2
	v_mov_b32_e32 v169, 0
	v_cmp_eq_u32_e64 s[8:9], 0, v2
	v_and_b32_e32 v3, 32, v204
	v_cmp_eq_u32_e64 s[4:5], 0, v3
	v_and_b32_e32 v3, 16, v204
	v_cmp_eq_u32_e64 s[6:7], 0, v3
	s_add_u32 s26, s94, 0x4008000
	s_addc_u32 s27, s95, 0
	s_add_u32 s30, s94, 0x8000
	s_addc_u32 s31, s95, 0
	s_add_u32 s28, s94, 0x1cb08000
	s_addc_u32 s29, s95, 0
	s_add_u32 s34, s94, 0x1cb18000
	s_addc_u32 s35, s95, 0
	s_mov_b64 s[40:41], 0x1000
	s_movk_i32 s67, 0x1000
	s_mov_b32 s3, 0xc0e00000
	v_mov_b32_e32 v183, 0x40e00000
	s_waitcnt lgkmcnt(0)
	v_lshl_add_u64 v[172:173], s[48:49], 0, v[0:1]
	v_lshl_add_u64 v[170:171], s[50:51], 0, v[0:1]
	s_add_u32 s50, s2, 0xffffff80
	s_lshl_b32 s50, s50, 1
	s_lshl_b32 s12, s50, 2
	v_lshl_or_b32 v34, s50, 4, v180
	s_mov_b32 s13, 0
	s_branch .LBB0_563_p4

.LBB0_567_p4:
	s_and_b64 vcc, exec, s[10:11]
	s_cbranch_vccz .LBB0_562_p4
	v_ashrrev_i32_e32 v35, 31, v34
	v_lshlrev_b64 v[2:3], 13, v[34:35]
	v_lshl_add_u64 v[2:3], v[172:173], 0, v[2:3]
	v_add_co_u32_e32 v4, vcc, s67, v2
	global_load_dwordx4 v[30:33], v[2:3], off
	global_load_dwordx4 v[26:29], v[2:3], off offset:16
	global_load_dwordx4 v[14:17], v[2:3], off offset:32
	global_load_dwordx4 v[6:9], v[2:3], off offset:48
	v_addc_co_u32_e32 v5, vcc, 0, v3, vcc
	global_load_dwordx4 v[18:21], v[4:5], off
	v_lshl_add_u64 v[2:3], v[2:3], 0, s[40:41]
	global_load_dwordx4 v[22:25], v[2:3], off offset:16
	global_load_dwordx4 v[10:13], v[2:3], off offset:32
	s_nop 0
	global_load_dwordx4 v[2:5], v[2:3], off offset:48
	s_waitcnt vmcnt(7)
	v_max_f32_e64 v0, |v33|, |v33|
	v_max_f32_e64 v36, |v32|, |v32|
	s_waitcnt vmcnt(6)
	v_max_f32_e64 v37, |v29|, |v29|
	v_max_f32_e64 v38, |v28|, |v28|
	s_waitcnt vmcnt(5)
	v_max_f32_e64 v39, |v17|, |v17|
	v_max_f32_e64 v40, |v16|, |v16|
	s_waitcnt vmcnt(4)
	v_max_f32_e64 v41, |v9|, |v9|
	v_max_f32_e64 v42, |v8|, |v8|
	v_max_f32_e32 v0, v36, v0
	v_max_f32_e32 v36, v38, v37
	v_max_f32_e32 v37, v40, v39
	v_max_f32_e32 v38, v42, v41
	s_waitcnt vmcnt(3)
	v_max_f32_e64 v39, |v21|, |v21|
	v_max_f32_e64 v40, |v20|, |v20|
	s_waitcnt vmcnt(2)
	v_max_f32_e64 v41, |v25|, |v25|
	v_max_f32_e64 v42, |v24|, |v24|
	v_max3_f32 v0, |v30|, |v31|, v0
	v_max3_f32 v36, |v26|, |v27|, v36
	s_waitcnt vmcnt(1)
	v_max_f32_e64 v43, |v13|, |v13|
	v_max_f32_e64 v44, |v12|, |v12|
	s_waitcnt vmcnt(0)
	v_max_f32_e64 v45, |v5|, |v5|
	v_max_f32_e64 v46, |v4|, |v4|
	v_max3_f32 v37, |v14|, |v15|, v37
	v_max3_f32 v38, |v6|, |v7|, v38
	v_max_f32_e32 v39, v40, v39
	v_max_f32_e32 v40, v42, v41
	v_max3_f32 v0, v0, 0, v36
	v_max_f32_e32 v41, v44, v43
	v_max_f32_e32 v42, v46, v45
	v_max3_f32 v36, |v18|, |v19|, v39
	v_max3_f32 v39, |v22|, |v23|, v40
	v_max3_f32 v0, v0, v37, v38
	v_max3_f32 v40, |v10|, |v11|, v41
	v_max3_f32 v41, |v2|, |v3|, v42
	v_max3_f32 v0, v0, v36, v39
	v_max3_f32 v0, v0, v40, v41
	v_mov_b32_e32 v36, v0
	v_mov_b32_e32 v37, v0
	s_nop 1
	v_permlane32_swap_b32_e32 v36, v37
	v_cndmask_b32_e64 v36, v36, v37, s[4:5]
	v_max_f32_e32 v36, v36, v36
	v_max_f32_e32 v0, v0, v36
	v_mov_b32_e32 v36, v0
	v_mov_b32_e32 v37, v0
	s_nop 1
	v_permlane16_swap_b32_e32 v36, v37
	v_cndmask_b32_e64 v36, v36, v37, s[6:7]
	v_max_f32_e32 v36, v36, v36
	v_max_f32_e32 v0, v0, v36
	s_nop 1
	v_mov_b32_dpp v36, v0 row_ror:8 row_mask:0xf bank_mask:0xf bound_ctrl:1
	v_max_f32_e32 v36, v36, v36
	v_max_f32_e32 v0, v0, v36
	s_nop 1
	v_mov_b32_dpp v36, v0 row_half_mirror row_mask:0xf bank_mask:0xf bound_ctrl:1
	s_nop 1
	v_mov_b32_dpp v36, v36 quad_perm:[3,2,1,0] row_mask:0xf bank_mask:0xf bound_ctrl:1
	v_max_f32_e32 v36, v36, v36
	v_max_f32_e32 v0, v0, v36
	s_nop 1
	v_mov_b32_dpp v36, v0 quad_perm:[2,3,0,1] row_mask:0xf bank_mask:0xf bound_ctrl:1
	v_max_f32_e32 v36, v36, v36
	v_max_f32_e32 v0, v0, v36
	s_nop 1
	v_mov_b32_dpp v36, v0 quad_perm:[1,0,3,2] row_mask:0xf bank_mask:0xf bound_ctrl:1
	v_max_f32_e32 v36, v36, v36
	v_max_f32_e32 v0, v0, v36
	v_mul_f32_e32 v36, 0x3e124925, v0
	v_cmp_lt_f32_e32 vcc, 0, v0
	s_nop 1
	v_cndmask_b32_e32 v0, 1.0, v36, vcc
	s_and_saveexec_b64 s[10:11], s[8:9]
	s_cbranch_execz .LBB0_561_p4
	v_lshl_add_u64 v[36:37], v[34:35], 2, s[34:35]
	global_store_dword v[36:37], v0, off
	s_branch .LBB0_561_p4
.Lcv_ret_p4:
	s_load_dwordx4 s[28:31], s[0:1], 0x110
	v_readlane_b32 s8, v244, 1
	v_readlane_b32 s9, v244, 2
	s_waitcnt lgkmcnt(0)
	s_cmp_lt_i32 s29, 6
	s_cselect_b64 s[6:7], -1, 0
	s_xor_b64 s[8:9], s[8:9], -1
	s_or_b64 s[6:7], s[6:7], s[8:9]
	s_and_b64 vcc, exec, s[6:7]
	s_cbranch_vccnz .LBB0_703
	s_waitcnt vmcnt(0)
	s_waitcnt vmcnt(63) expcnt(7) lgkmcnt(15)
	s_barrier
	s_and_saveexec_b64 s[6:7], s[56:57]
	s_cbranch_execz .LBB0_702
	v_readlane_b32 s8, v244, 0
	s_waitcnt vmcnt(0) expcnt(0) lgkmcnt(0)
	s_nop 0
	v_mov_b32_e32 v0, s8
	ds_read_b32 v2, v0
	ds_read_b32 v0, v0 offset:4
	s_waitcnt lgkmcnt(1)
	v_cmp_ne_u32_e32 vcc, 0, v2
	s_cbranch_vccnz .LBB0_673
	s_load_dwordx2 s[10:11], s[4:5], 0x4
	s_add_u32 s4, s58, 0x1000
	s_addc_u32 s5, s59, 0
	s_add_u32 s8, s58, 0x1100
	s_addc_u32 s9, s59, 0
	s_waitcnt lgkmcnt(0)
	s_mul_i32 s3, s10, s3
	s_add_u32 s10, s58, 0x1200
	s_mul_i32 s3, s3, s11
	s_addc_u32 s11, s59, 0
	s_add_u32 s12, s58, 0x1300
	s_addc_u32 s13, s59, 0
	s_mov_b32 s20, 1
	v_mov_b32_e32 v16, 0
	s_branch .LBB0_663

.LBB0_738:
	s_cmp_lt_u32 s2, 0x80
	s_cbranch_scc1 .Lcv_ret_p5
	s_load_dwordx4 s[48:51], s[0:1], 0xf0
	v_mov_b32_e32 v1, 0
	v_and_b32_e32 v2, 63, v204
	v_lshlrev_b32_e32 v0, 6, v2
	v_lshrrev_b32_e32 v180, 6, v204
	v_lshlrev_b32_e32 v168, 3, v2
	v_mov_b32_e32 v169, 0
	v_cmp_eq_u32_e64 s[8:9], 0, v2
	v_and_b32_e32 v3, 32, v204
	v_cmp_eq_u32_e64 s[4:5], 0, v3
	v_and_b32_e32 v3, 16, v204
	v_cmp_eq_u32_e64 s[6:7], 0, v3
	s_add_u32 s26, s94, 0x4008000
	s_addc_u32 s27, s95, 0
	s_add_u32 s30, s94, 0x8000
	s_addc_u32 s31, s95, 0
	s_add_u32 s28, s94, 0x1cb08000
	s_addc_u32 s29, s95, 0
	s_add_u32 s34, s94, 0x1cb18000
	s_addc_u32 s35, s95, 0
	s_mov_b64 s[40:41], 0x1000
	s_movk_i32 s67, 0x1000
	s_mov_b32 s3, 0xc0e00000
	v_mov_b32_e32 v183, 0x40e00000
	s_waitcnt lgkmcnt(0)
	v_lshl_add_u64 v[172:173], s[48:49], 0, v[0:1]
	v_lshl_add_u64 v[170:171], s[50:51], 0, v[0:1]
	s_add_u32 s50, s2, 0x100
	s_lshl_b32 s50, s50, 1
	s_lshl_b32 s12, s50, 2
	v_lshl_or_b32 v34, s50, 4, v180
	s_mov_b32 s13, 0
	s_branch .LBB0_563_p5

.LBB0_567_p5:
	s_and_b64 vcc, exec, s[10:11]
	s_cbranch_vccz .LBB0_562_p5
	v_ashrrev_i32_e32 v35, 31, v34
	v_lshlrev_b64 v[2:3], 13, v[34:35]
	v_lshl_add_u64 v[2:3], v[172:173], 0, v[2:3]
	v_add_co_u32_e32 v4, vcc, s67, v2
	global_load_dwordx4 v[30:33], v[2:3], off
	global_load_dwordx4 v[26:29], v[2:3], off offset:16
	global_load_dwordx4 v[14:17], v[2:3], off offset:32
	global_load_dwordx4 v[6:9], v[2:3], off offset:48
	v_addc_co_u32_e32 v5, vcc, 0, v3, vcc
	global_load_dwordx4 v[18:21], v[4:5], off
	v_lshl_add_u64 v[2:3], v[2:3], 0, s[40:41]
	global_load_dwordx4 v[22:25], v[2:3], off offset:16
	global_load_dwordx4 v[10:13], v[2:3], off offset:32
	s_nop 0
	global_load_dwordx4 v[2:5], v[2:3], off offset:48
	s_waitcnt vmcnt(7)
	v_max_f32_e64 v0, |v33|, |v33|
	v_max_f32_e64 v36, |v32|, |v32|
	s_waitcnt vmcnt(6)
	v_max_f32_e64 v37, |v29|, |v29|
	v_max_f32_e64 v38, |v28|, |v28|
	s_waitcnt vmcnt(5)
	v_max_f32_e64 v39, |v17|, |v17|
	v_max_f32_e64 v40, |v16|, |v16|
	s_waitcnt vmcnt(4)
	v_max_f32_e64 v41, |v9|, |v9|
	v_max_f32_e64 v42, |v8|, |v8|
	v_max_f32_e32 v0, v36, v0
	v_max_f32_e32 v36, v38, v37
	v_max_f32_e32 v37, v40, v39
	v_max_f32_e32 v38, v42, v41
	s_waitcnt vmcnt(3)
	v_max_f32_e64 v39, |v21|, |v21|
	v_max_f32_e64 v40, |v20|, |v20|
	s_waitcnt vmcnt(2)
	v_max_f32_e64 v41, |v25|, |v25|
	v_max_f32_e64 v42, |v24|, |v24|
	v_max3_f32 v0, |v30|, |v31|, v0
	v_max3_f32 v36, |v26|, |v27|, v36
	s_waitcnt vmcnt(1)
	v_max_f32_e64 v43, |v13|, |v13|
	v_max_f32_e64 v44, |v12|, |v12|
	s_waitcnt vmcnt(0)
	v_max_f32_e64 v45, |v5|, |v5|
	v_max_f32_e64 v46, |v4|, |v4|
	v_max3_f32 v37, |v14|, |v15|, v37
	v_max3_f32 v38, |v6|, |v7|, v38
	v_max_f32_e32 v39, v40, v39
	v_max_f32_e32 v40, v42, v41
	v_max3_f32 v0, v0, 0, v36
	v_max_f32_e32 v41, v44, v43
	v_max_f32_e32 v42, v46, v45
	v_max3_f32 v36, |v18|, |v19|, v39
	v_max3_f32 v39, |v22|, |v23|, v40
	v_max3_f32 v0, v0, v37, v38
	v_max3_f32 v40, |v10|, |v11|, v41
	v_max3_f32 v41, |v2|, |v3|, v42
	v_max3_f32 v0, v0, v36, v39
	v_max3_f32 v0, v0, v40, v41
	v_mov_b32_e32 v36, v0
	v_mov_b32_e32 v37, v0
	s_nop 1
	v_permlane32_swap_b32_e32 v36, v37
	v_cndmask_b32_e64 v36, v36, v37, s[4:5]
	v_max_f32_e32 v36, v36, v36
	v_max_f32_e32 v0, v0, v36
	v_mov_b32_e32 v36, v0
	v_mov_b32_e32 v37, v0
	s_nop 1
	v_permlane16_swap_b32_e32 v36, v37
	v_cndmask_b32_e64 v36, v36, v37, s[6:7]
	v_max_f32_e32 v36, v36, v36
	v_max_f32_e32 v0, v0, v36
	s_nop 1
	v_mov_b32_dpp v36, v0 row_ror:8 row_mask:0xf bank_mask:0xf bound_ctrl:1
	v_max_f32_e32 v36, v36, v36
	v_max_f32_e32 v0, v0, v36
	s_nop 1
	v_mov_b32_dpp v36, v0 row_half_mirror row_mask:0xf bank_mask:0xf bound_ctrl:1
	s_nop 1
	v_mov_b32_dpp v36, v36 quad_perm:[3,2,1,0] row_mask:0xf bank_mask:0xf bound_ctrl:1
	v_max_f32_e32 v36, v36, v36
	v_max_f32_e32 v0, v0, v36
	s_nop 1
	v_mov_b32_dpp v36, v0 quad_perm:[2,3,0,1] row_mask:0xf bank_mask:0xf bound_ctrl:1
	v_max_f32_e32 v36, v36, v36
	v_max_f32_e32 v0, v0, v36
	s_nop 1
	v_mov_b32_dpp v36, v0 quad_perm:[1,0,3,2] row_mask:0xf bank_mask:0xf bound_ctrl:1
	v_max_f32_e32 v36, v36, v36
	v_max_f32_e32 v0, v0, v36
	v_mul_f32_e32 v36, 0x3e124925, v0
	v_cmp_lt_f32_e32 vcc, 0, v0
	s_nop 1
	v_cndmask_b32_e32 v0, 1.0, v36, vcc
	s_and_saveexec_b64 s[10:11], s[8:9]
	s_cbranch_execz .LBB0_561_p5
	v_lshl_add_u64 v[36:37], v[34:35], 2, s[34:35]
	global_store_dword v[36:37], v0, off
	s_branch .LBB0_561_p5
.Lcv_ret_p5:
	s_load_dwordx4 s[28:31], s[0:1], 0x110
	v_readlane_b32 s8, v244, 1
	v_readlane_b32 s9, v244, 2
	s_waitcnt lgkmcnt(0)
	s_cmp_lt_i32 s29, 7
	s_cselect_b64 s[6:7], -1, 0
	s_xor_b64 s[8:9], s[8:9], -1
	s_or_b64 s[6:7], s[6:7], s[8:9]
	s_and_b64 vcc, exec, s[6:7]
	s_cbranch_vccnz .LBB0_783
	s_waitcnt vmcnt(0)
	s_waitcnt vmcnt(63) expcnt(7) lgkmcnt(15)
	s_barrier
	s_and_saveexec_b64 s[6:7], s[56:57]
	s_cbranch_execz .LBB0_782
	v_readlane_b32 s8, v244, 0
	s_waitcnt vmcnt(0) expcnt(0) lgkmcnt(0)
	s_nop 0
	v_mov_b32_e32 v0, s8
	ds_read_b32 v2, v0
	ds_read_b32 v0, v0 offset:4
	s_waitcnt lgkmcnt(1)
	v_cmp_ne_u32_e32 vcc, 0, v2
	s_cbranch_vccnz .LBB0_753
	v_readlane_b32 s4, v244, 4
	v_readlane_b32 s5, v244, 5
	s_load_dwordx2 s[10:11], s[4:5], 0x4
	s_load_dword s3, s[0:1], 0x120
	s_add_u32 s4, s58, 0x1000
	s_addc_u32 s5, s59, 0
	s_add_u32 s8, s58, 0x1100
	s_addc_u32 s9, s59, 0
	s_waitcnt lgkmcnt(0)
	s_mul_i32 s3, s10, s3
	s_add_u32 s10, s58, 0x1200
	s_mul_i32 s3, s3, s11
	s_addc_u32 s11, s59, 0
	s_add_u32 s12, s58, 0x1300
	s_addc_u32 s13, s59, 0
	s_mov_b32 s20, 1
	v_mov_b32_e32 v16, 0
	s_branch .LBB0_743

.LBB0_811:
	s_cmp_lt_u32 s2, 0x100
	s_cbranch_scc1 .Lcv_ret_p6
	s_load_dwordx4 s[48:51], s[0:1], 0xf0
	v_mov_b32_e32 v1, 0
	v_and_b32_e32 v2, 63, v204
	v_lshlrev_b32_e32 v0, 6, v2
	v_lshrrev_b32_e32 v180, 6, v204
	v_lshlrev_b32_e32 v168, 3, v2
	v_mov_b32_e32 v169, 0
	v_cmp_eq_u32_e64 s[8:9], 0, v2
	v_and_b32_e32 v3, 32, v204
	v_cmp_eq_u32_e64 s[4:5], 0, v3
	v_and_b32_e32 v3, 16, v204
	v_cmp_eq_u32_e64 s[6:7], 0, v3
	s_add_u32 s26, s94, 0x4008000
	s_addc_u32 s27, s95, 0
	s_add_u32 s30, s94, 0x8000
	s_addc_u32 s31, s95, 0
	s_add_u32 s28, s94, 0x1cb08000
	s_addc_u32 s29, s95, 0
	s_add_u32 s34, s94, 0x1cb18000
	s_addc_u32 s35, s95, 0
	s_mov_b64 s[40:41], 0x1000
	s_movk_i32 s67, 0x1000
	s_mov_b32 s3, 0xc0e00000
	v_mov_b32_e32 v183, 0x40e00000
	s_waitcnt lgkmcnt(0)
	v_lshl_add_u64 v[172:173], s[48:49], 0, v[0:1]
	v_lshl_add_u64 v[170:171], s[50:51], 0, v[0:1]
	s_add_u32 s50, s2, 0x200
	s_lshl_b32 s50, s50, 1
	s_lshl_b32 s12, s50, 2
	v_lshl_or_b32 v34, s50, 4, v180
	s_mov_b32 s13, 0
	s_branch .LBB0_563_p6

.LBB0_567_p6:
	s_and_b64 vcc, exec, s[10:11]
	s_cbranch_vccz .LBB0_562_p6
	v_ashrrev_i32_e32 v35, 31, v34
	v_lshlrev_b64 v[2:3], 13, v[34:35]
	v_lshl_add_u64 v[2:3], v[172:173], 0, v[2:3]
	v_add_co_u32_e32 v4, vcc, s67, v2
	global_load_dwordx4 v[30:33], v[2:3], off
	global_load_dwordx4 v[26:29], v[2:3], off offset:16
	global_load_dwordx4 v[14:17], v[2:3], off offset:32
	global_load_dwordx4 v[6:9], v[2:3], off offset:48
	v_addc_co_u32_e32 v5, vcc, 0, v3, vcc
	global_load_dwordx4 v[18:21], v[4:5], off
	v_lshl_add_u64 v[2:3], v[2:3], 0, s[40:41]
	global_load_dwordx4 v[22:25], v[2:3], off offset:16
	global_load_dwordx4 v[10:13], v[2:3], off offset:32
	s_nop 0
	global_load_dwordx4 v[2:5], v[2:3], off offset:48
	s_waitcnt vmcnt(7)
	v_max_f32_e64 v0, |v33|, |v33|
	v_max_f32_e64 v36, |v32|, |v32|
	s_waitcnt vmcnt(6)
	v_max_f32_e64 v37, |v29|, |v29|
	v_max_f32_e64 v38, |v28|, |v28|
	s_waitcnt vmcnt(5)
	v_max_f32_e64 v39, |v17|, |v17|
	v_max_f32_e64 v40, |v16|, |v16|
	s_waitcnt vmcnt(4)
	v_max_f32_e64 v41, |v9|, |v9|
	v_max_f32_e64 v42, |v8|, |v8|
	v_max_f32_e32 v0, v36, v0
	v_max_f32_e32 v36, v38, v37
	v_max_f32_e32 v37, v40, v39
	v_max_f32_e32 v38, v42, v41
	s_waitcnt vmcnt(3)
	v_max_f32_e64 v39, |v21|, |v21|
	v_max_f32_e64 v40, |v20|, |v20|
	s_waitcnt vmcnt(2)
	v_max_f32_e64 v41, |v25|, |v25|
	v_max_f32_e64 v42, |v24|, |v24|
	v_max3_f32 v0, |v30|, |v31|, v0
	v_max3_f32 v36, |v26|, |v27|, v36
	s_waitcnt vmcnt(1)
	v_max_f32_e64 v43, |v13|, |v13|
	v_max_f32_e64 v44, |v12|, |v12|
	s_waitcnt vmcnt(0)
	v_max_f32_e64 v45, |v5|, |v5|
	v_max_f32_e64 v46, |v4|, |v4|
	v_max3_f32 v37, |v14|, |v15|, v37
	v_max3_f32 v38, |v6|, |v7|, v38
	v_max_f32_e32 v39, v40, v39
	v_max_f32_e32 v40, v42, v41
	v_max3_f32 v0, v0, 0, v36
	v_max_f32_e32 v41, v44, v43
	v_max_f32_e32 v42, v46, v45
	v_max3_f32 v36, |v18|, |v19|, v39
	v_max3_f32 v39, |v22|, |v23|, v40
	v_max3_f32 v0, v0, v37, v38
	v_max3_f32 v40, |v10|, |v11|, v41
	v_max3_f32 v41, |v2|, |v3|, v42
	v_max3_f32 v0, v0, v36, v39
	v_max3_f32 v0, v0, v40, v41
	v_mov_b32_e32 v36, v0
	v_mov_b32_e32 v37, v0
	s_nop 1
	v_permlane32_swap_b32_e32 v36, v37
	v_cndmask_b32_e64 v36, v36, v37, s[4:5]
	v_max_f32_e32 v36, v36, v36
	v_max_f32_e32 v0, v0, v36
	v_mov_b32_e32 v36, v0
	v_mov_b32_e32 v37, v0
	s_nop 1
	v_permlane16_swap_b32_e32 v36, v37
	v_cndmask_b32_e64 v36, v36, v37, s[6:7]
	v_max_f32_e32 v36, v36, v36
	v_max_f32_e32 v0, v0, v36
	s_nop 1
	v_mov_b32_dpp v36, v0 row_ror:8 row_mask:0xf bank_mask:0xf bound_ctrl:1
	v_max_f32_e32 v36, v36, v36
	v_max_f32_e32 v0, v0, v36
	s_nop 1
	v_mov_b32_dpp v36, v0 row_half_mirror row_mask:0xf bank_mask:0xf bound_ctrl:1
	s_nop 1
	v_mov_b32_dpp v36, v36 quad_perm:[3,2,1,0] row_mask:0xf bank_mask:0xf bound_ctrl:1
	v_max_f32_e32 v36, v36, v36
	v_max_f32_e32 v0, v0, v36
	s_nop 1
	v_mov_b32_dpp v36, v0 quad_perm:[2,3,0,1] row_mask:0xf bank_mask:0xf bound_ctrl:1
	v_max_f32_e32 v36, v36, v36
	v_max_f32_e32 v0, v0, v36
	s_nop 1
	v_mov_b32_dpp v36, v0 quad_perm:[1,0,3,2] row_mask:0xf bank_mask:0xf bound_ctrl:1
	v_max_f32_e32 v36, v36, v36
	v_max_f32_e32 v0, v0, v36
	v_mul_f32_e32 v36, 0x3e124925, v0
	v_cmp_lt_f32_e32 vcc, 0, v0
	s_nop 1
	v_cndmask_b32_e32 v0, 1.0, v36, vcc
	s_and_saveexec_b64 s[10:11], s[8:9]
	s_cbranch_execz .LBB0_561_p6
	v_lshl_add_u64 v[36:37], v[34:35], 2, s[34:35]
	global_store_dword v[36:37], v0, off
	s_branch .LBB0_561_p6
.Lcv_ret_p6:
	s_load_dwordx4 s[28:31], s[0:1], 0x110
	v_readlane_b32 s8, v244, 1
	v_readlane_b32 s9, v244, 2
	s_waitcnt lgkmcnt(0)
	s_cmp_lt_i32 s29, 8
	s_cselect_b64 s[6:7], -1, 0
	s_xor_b64 s[8:9], s[8:9], -1
	s_or_b64 s[6:7], s[6:7], s[8:9]
	s_and_b64 vcc, exec, s[6:7]
	s_cbranch_vccnz .LBB0_856
	s_waitcnt vmcnt(0)
	s_waitcnt vmcnt(63) expcnt(7) lgkmcnt(15)
	s_barrier
	s_and_saveexec_b64 s[6:7], s[56:57]
	s_cbranch_execz .LBB0_855
	v_readlane_b32 s8, v244, 0
	s_waitcnt vmcnt(0) expcnt(0) lgkmcnt(0)
	s_nop 0
	v_mov_b32_e32 v0, s8
	ds_read_b32 v2, v0
	ds_read_b32 v0, v0 offset:4
	s_waitcnt lgkmcnt(1)
	v_cmp_ne_u32_e32 vcc, 0, v2
	s_cbranch_vccnz .LBB0_826
	s_load_dwordx2 s[10:11], s[4:5], 0x4
	s_add_u32 s4, s58, 0x1000
	s_addc_u32 s5, s59, 0
	s_add_u32 s8, s58, 0x1100
	s_addc_u32 s9, s59, 0
	s_waitcnt lgkmcnt(0)
	s_mul_i32 s3, s10, s3
	s_add_u32 s10, s58, 0x1200
	s_mul_i32 s3, s3, s11
	s_addc_u32 s11, s59, 0
	s_add_u32 s12, s58, 0x1300
	s_addc_u32 s13, s59, 0
	s_mov_b32 s20, 1
	v_mov_b32_e32 v16, 0
	s_branch .LBB0_816
